# speedup vs baseline: 1.0147x; 1.0005x over previous
; __device__ __forceinline__ StreamInfo stream_of(int m0) { StreamInfo r; if (m0 < MP) { r.s = m0 / TP; r.t0 = m0 % TP; r.T = TP; r.sample = false; } else { const int q = m0 - MP; r.s = q / TS; r.t0 = q % TS; r.T = TS; r.sample = true; } return r; }
; __device__ __forceinline__ void post_phase(const bf16* P, const bf16* LOUT, const float* mu, const float* k_a, const float* r_k, const float* ln_w, const float* ln_b, const float* cache_shift, bf16* MIX, int gw, int NGW, int lane) {
;     for (int item = gw; item < M * 4; item += NGW) {
;         const int m = item >> 2, hg = item & 3, ch = hg * 256 + lane * 4;
;         const StreamInfo si = stream_of(m);
;         const bf16* pr = P + (size_t)m * PROJ + 3 * CONVC + ch;
;         const f32x4 y = *(const f32x4*)((const float*)(P + (size_t)m * PROJ) + ch);
;         const u32x2 r1 = *(const u32x2*)pr, k1 = *(const u32x2*)(pr + RW), v1 = *(const u32x2*)(pr + 2 * RW);
;         f32x4 r0, k0, v0;
;         if (si.t0 > 0) { const u32x2 a = *(const u32x2*)(pr - PROJ), b = *(const u32x2*)(pr - PROJ + RW), c = *(const u32x2*)(pr - PROJ + 2 * RW);
;             r0 = (f32x4){bflo(a.x), bfhi(a.x), bflo(a.y), bfhi(a.y)}; k0 = (f32x4){bflo(b.x), bfhi(b.x), bflo(b.y), bfhi(b.y)}; v0 = (f32x4){bflo(c.x), bfhi(c.x), bflo(c.y), bfhi(c.y)}; }
;         else if (si.sample) { const float* sp = cache_shift + (size_t)si.s * SHIFT + ch; r0 = *(const f32x4*)sp; k0 = *(const f32x4*)(sp + RW); v0 = *(const f32x4*)(sp + 2 * RW); }
;         else { r0 = k0 = v0 = (f32x4){0.f, 0.f, 0.f, 0.f}; }
;         const u32x2 aw = *(const u32x2*)(LOUT + (size_t)m * LN + RW + ch), gw_ = *(const u32x2*)(LOUT + (size_t)m * LN + 2 * RW + ch);
;         const f32x4 rc = (f32x4){bflo(r1.x), bfhi(r1.x), bflo(r1.y), bfhi(r1.y)}, kc = (f32x4){bflo(k1.x), bfhi(k1.x), bflo(k1.y), bfhi(k1.y)}, vc = (f32x4){bflo(v1.x), bfhi(v1.x), bflo(v1.y), bfhi(v1.y)};
;         const f32x4 a = (f32x4){bflo(aw.x), bfhi(aw.x), bflo(aw.y), bfhi(aw.y)}, g = (f32x4){bflo(gw_.x), bfhi(gw_.x), bflo(gw_.y), bfhi(gw_.y)};
;         const f32x4 mur = *(const f32x4*)(mu + ch), muk = *(const f32x4*)(mu + RW + ch), muv = *(const f32x4*)(mu + 2 * RW + ch), ka = *(const f32x4*)(k_a + ch), rk = *(const f32x4*)(r_k + ch), lw = *(const f32x4*)(ln_w + ch), lb = *(const f32x4*)(ln_b + ch);
.LBB0_915:
	s_mov_b64 s[24:25], s[0:1]
	s_cmp_gt_i32 s34, 0x10fff
	s_waitcnt lgkmcnt(0)
	s_cbranch_scc1 .LBB0_928
	s_load_dwordx2 s[4:5], s[24:25], 0x100
	s_load_dwordx8 s[12:19], s[24:25], 0xa0
	s_load_dwordx2 s[6:7], s[24:25], 0x68
	s_load_dwordx2 s[8:9], s[24:25], 0x18
	v_lshlrev_b32_e32 v1, 2, v166
	s_waitcnt lgkmcnt(0)
	s_add_u32 s33, s4, 0xa8c0000
	s_addc_u32 s35, s5, 0
	s_add_u32 s37, s4, 0x18b10000
	s_addc_u32 s42, s5, 0
	s_add_u32 s24, s6, 0x1000
	s_addc_u32 s25, s7, 0
	s_add_u32 s26, s6, 0x2000
	s_addc_u32 s27, s7, 0
	s_lshl_b32 s10, s2, 11
	s_lshl_b32 s3, s3, 8
	s_add_i32 s3, s10, s3
	s_lshl_b32 s43, s40, 11
	s_waitcnt vmcnt(0)
	v_mov_b32_e32 v19, 0
	s_mov_b64 s[28:29], 0x1800
	s_movk_i32 s50, 0x1000
	v_mov_b32_e32 v30, 0x3a27c5ac
	s_mov_b32 s51, s34
	s_and_b32 s10, s3, 0x300
	v_or_b32_e32 v2, s10, v1
	v_lshlrev_b32_e32 v20, 2, v2
	global_load_dwordx4 v[72:75], v20, s[6:7]
	global_load_dwordx4 v[76:79], v20, s[24:25]
	global_load_dwordx4 v[80:83], v20, s[26:27]
	global_load_dwordx4 v[84:87], v20, s[12:13]
	global_load_dwordx4 v[88:91], v20, s[14:15]
	global_load_dwordx4 v[92:95], v20, s[16:17]
	global_load_dwordx4 v[96:99], v20, s[18:19]

; __device__ __forceinline__ StreamInfo stream_of(int m0) { StreamInfo r; if (m0 < MP) { r.s = m0 / TP; r.t0 = m0 % TP; r.T = TP; r.sample = false; } else { const int q = m0 - MP; r.s = q / TS; r.t0 = q % TS; r.T = TS; r.sample = true; } return r; }
; __device__ __forceinline__ void post_phase(const bf16* P, const bf16* LOUT, const float* mu, const float* k_a, const float* r_k, const float* ln_w, const float* ln_b, const float* cache_shift, bf16* MIX, int gw, int NGW, int lane) {
;     ...
;         const StreamInfo si = stream_of(m);
;         const bf16* pr = P + (size_t)m * PROJ + 3 * CONVC + ch;
;         const f32x4 y = *(const f32x4*)((const float*)(P + (size_t)m * PROJ) + ch);
;         const u32x2 r1 = *(const u32x2*)pr, k1 = *(const u32x2*)(pr + RW), v1 = *(const u32x2*)(pr + 2 * RW);
;         f32x4 r0, k0, v0;
;         if (si.t0 > 0) { const u32x2 a = *(const u32x2*)(pr - PROJ), b = *(const u32x2*)(pr - PROJ + RW), c = *(const u32x2*)(pr - PROJ + 2 * RW);
;             r0 = (f32x4){bflo(a.x), bfhi(a.x), bflo(a.y), bfhi(a.y)}; k0 = (f32x4){bflo(b.x), bfhi(b.x), bflo(b.y), bfhi(b.y)}; v0 = (f32x4){bflo(c.x), bfhi(c.x), bflo(c.y), bfhi(c.y)}; }
;         else if (si.sample) { const float* sp = cache_shift + (size_t)si.s * SHIFT + ch; r0 = *(const f32x4*)sp; k0 = *(const f32x4*)(sp + RW); v0 = *(const f32x4*)(sp + 2 * RW); }
;         else { r0 = k0 = v0 = (f32x4){0.f, 0.f, 0.f, 0.f}; }
;         const u32x2 aw = *(const u32x2*)(LOUT + (size_t)m * LN + RW + ch), gw_ = *(const u32x2*)(LOUT + (size_t)m * LN + 2 * RW + ch);
;         const f32x4 rc = (f32x4){bflo(r1.x), bfhi(r1.x), bflo(r1.y), bfhi(r1.y)}, kc = (f32x4){bflo(k1.x), bfhi(k1.x), bflo(k1.y), bfhi(k1.y)}, vc = (f32x4){bflo(v1.x), bfhi(v1.x), bflo(v1.y), bfhi(v1.y)};
;         const f32x4 a = (f32x4){bflo(aw.x), bfhi(aw.x), bflo(aw.y), bfhi(aw.y)}, g = (f32x4){bflo(gw_.x), bfhi(gw_.x), bflo(gw_.y), bfhi(gw_.y)};
.LBB0_922:
	s_and_b32 s10, s3, 0x300
	s_mul_i32 s11, s30, 0x3240
	v_or_b32_e32 v2, s10, v1
	s_mul_hi_i32 s10, s30, 0x3240
	s_add_u32 s48, s33, s11
	s_addc_u32 s49, s35, s10
	v_lshlrev_b32_e32 v18, 1, v2
	v_lshlrev_b32_e32 v20, 2, v2
	v_lshl_add_u64 v[32:33], s[48:49], 0, v[18:19]
	global_load_dwordx4 v[2:5], v20, s[48:49]
	v_lshl_add_u64 v[34:35], v[32:33], 0, s[28:29]
	v_lshl_add_u64 v[36:37], v[34:35], 0, s[28:29]
	global_load_dwordx2 v[26:27], v[34:35], off
	global_load_dwordx2 v[24:25], v[34:35], off offset:2048
	global_load_dwordx2 v[22:23], v[36:37], off offset:-2048
	s_cmp_lt_i32 s52, 1
	s_cbranch_scc0 .Lpost_prev
	v_mov_b32_e32 v9, 0
	v_mov_b32_e32 v8, 0
	v_mov_b32_e32 v7, 0
	v_mov_b32_e32 v6, 0
	v_mov_b32_e32 v13, 0
	v_mov_b32_e32 v12, 0
	v_mov_b32_e32 v11, 0
	v_mov_b32_e32 v10, 0
	v_mov_b32_e32 v17, 0
	v_mov_b32_e32 v16, 0
	v_mov_b32_e32 v15, 0
	v_mov_b32_e32 v14, 0
	s_andn2_b64 vcc, exec, s[46:47]
	s_cbranch_vccnz .Lpost_lout
	s_mul_i32 s11, s31, 0x3480
	s_mul_hi_i32 s10, s31, 0x3480
	s_add_u32 s46, s8, s11
	s_addc_u32 s47, s9, s10
	v_mov_b32_e32 v21, v19
	v_lshl_add_u64 v[10:11], s[46:47], 0, v[20:21]
	v_add_co_u32_e32 v12, vcc, 0x1000, v10
	global_load_dwordx4 v[6:9], v20, s[46:47]
	s_nop 0
	v_addc_co_u32_e32 v13, vcc, 0, v11, vcc
	v_add_co_u32_e32 v14, vcc, 0x2000, v10
	s_nop 1
	v_addc_co_u32_e32 v15, vcc, 0, v11, vcc
	global_load_dwordx4 v[10:13], v[12:13], off
	s_nop 0
	global_load_dwordx4 v[14:17], v[14:15], off
	s_branch .Lpost_lout
.Lpost_prev:
	v_add_co_u32_e32 v38, vcc, 0xffffe800, v32
	s_nop 1
	v_addc_co_u32_e32 v39, vcc, -1, v33, vcc
	global_load_dwordx2 v[42:43], v[38:39], off offset:-576
	global_load_dwordx2 v[44:45], v[38:39], off offset:1472
	global_load_dwordx2 v[46:47], v[38:39], off offset:3520
.Lpost_lout:
	s_ashr_i32 s31, s30, 31
	s_mul_i32 s11, s30, 0x1800
	s_mul_hi_i32 s10, s30, 0x1800
	s_add_u32 s46, s37, s11
	s_addc_u32 s47, s42, s10
	global_load_dwordx2 v[56:57], v18, s[46:47] offset:2048
	v_lshl_add_u64 v[40:41], s[46:47], 0, v[18:19]
	v_add_co_u32_e32 v40, vcc, s50, v40
	s_nop 1
	v_addc_co_u32_e32 v41, vcc, 0, v41, vcc
	global_load_dwordx2 v[58:59], v[40:41], off
	s_waitcnt vmcnt(0)
	s_cmp_lt_i32 s52, 1
	s_cbranch_scc1 .Lpost_compute
	v_lshlrev_b32_e32 v6, 16, v42
	v_and_b32_e32 v7, 0xffff0000, v42
	v_lshlrev_b32_e32 v8, 16, v43
	v_and_b32_e32 v9, 0xffff0000, v43
	v_lshlrev_b32_e32 v10, 16, v44
	v_and_b32_e32 v11, 0xffff0000, v44
	v_lshlrev_b32_e32 v12, 16, v45
	v_and_b32_e32 v13, 0xffff0000, v45
	v_lshlrev_b32_e32 v14, 16, v46
	v_and_b32_e32 v15, 0xffff0000, v46
	v_lshlrev_b32_e32 v16, 16, v47
	v_and_b32_e32 v17, 0xffff0000, v47
; __device__ __forceinline__ unsigned pk2(float lo, float hi) { return pg8::cvt_pk_bf16(lo, hi); }
; __device__ __forceinline__ float red16(float v) { v += dpp_mov<0xB1>(v); v += dpp_mov<0x4E>(v); v += dpp_mov<0x141>(v); v += dpp_mov<0x140>(v); return v; }
; __device__ __forceinline__ void post_phase(const bf16* P, const bf16* LOUT, const float* mu, const float* k_a, const float* r_k, const float* ln_w, const float* ln_b, const float* cache_shift, bf16* MIX, int gw, int NGW, int lane) {
;     ...
;         const f32x4 r = rc + (r0 - rc) * mur, k = kc + (k0 - kc) * muk, v = vc + (v0 - vc) * muv;
;         const f32x4 k2 = k * (1.f + (a - 1.f) * ka), q = r * k2 * rk;
;         const float rkr = red16((q[0] + q[1]) + (q[2] + q[3]));
;         const float mean = red16((y[0] + y[1]) + (y[2] + y[3])) * (1.f / 64.f);
;         const f32x4 d = y - mean;
;         const float var = red16((d[0] * d[0] + d[1] * d[1]) + (d[2] * d[2] + d[3] * d[3])) * (1.f / 64.f);
;         const float rs = __builtin_amdgcn_rsqf(var + GN_EPS);
;         const f32x4 o = ((d * rs) * lw + lb + rkr * v) * g;
;         u32x2 w; w.x = pk2(o[0], o[1]); w.y = pk2(o[2], o[3]);
;         *(u32x2*)(MIX + (size_t)m * DM + CONVC + ch) = w;
.Lpost_compute:
	v_lshlrev_b32_e32 v60, 16, v26
	v_and_b32_e32 v61, 0xffff0000, v26
	v_lshlrev_b32_e32 v62, 16, v27
	v_and_b32_e32 v63, 0xffff0000, v27
	v_mov_b32_e32 v66, v3
	v_mov_b32_e32 v67, v4
	v_mov_b32_e32 v68, v2
	v_mov_b32_e32 v69, v5
	v_pk_add_f32 v[66:67], v[66:67], v[68:69]
	v_lshlrev_b32_e32 v64, 16, v24
	v_add_f32_e32 v31, v66, v67
	v_and_b32_e32 v65, 0xffff0000, v24
	v_lshlrev_b32_e32 v20, 16, v25
	v_and_b32_e32 v21, 0xffff0000, v25
	v_lshlrev_b32_e32 v24, 16, v22
	v_and_b32_e32 v25, 0xffff0000, v22
	v_lshlrev_b32_e32 v22, 16, v23
	v_and_b32_e32 v23, 0xffff0000, v23
	v_add_f32_dpp v31, v31, v31 quad_perm:[1,0,3,2] row_mask:0xf bank_mask:0xf bound_ctrl:1
	v_sub_f32_e32 v13, v13, v21
	v_sub_f32_e32 v12, v12, v20
	v_sub_f32_e32 v17, v17, v23
	v_sub_f32_e32 v16, v16, v22
	v_add_f32_dpp v31, v31, v31 quad_perm:[2,3,0,1] row_mask:0xf bank_mask:0xf bound_ctrl:1
	v_sub_f32_e32 v11, v11, v65
	v_sub_f32_e32 v10, v10, v64
	v_add_f32_dpp v31, v31, v31 row_half_mirror row_mask:0xf bank_mask:0xf bound_ctrl:1
	v_sub_f32_e32 v7, v7, v61
	v_sub_f32_e32 v6, v6, v60
	v_add_f32_dpp v31, v31, v31 row_mirror row_mask:0xf bank_mask:0xf bound_ctrl:1
	v_sub_f32_e32 v9, v9, v63
	v_sub_f32_e32 v8, v8, v62
	v_fmamk_f32 v3, v31, 0xbc800000, v3
	v_fmamk_f32 v2, v31, 0xbc800000, v2
	v_fmamk_f32 v5, v31, 0xbc800000, v5
	v_fmac_f32_e32 v4, 0xbc800000, v31
	v_pk_mul_f32 v[66:67], v[4:5], v[4:5]
	v_pk_mul_f32 v[68:69], v[2:3], v[2:3]
	v_sub_f32_e32 v15, v15, v25
	v_pk_mov_b32 v[70:71], v[68:69], v[66:67] op_sel:[1,0]
	v_mov_b32_e32 v69, v67
	v_pk_add_f32 v[66:67], v[70:71], v[68:69]
	v_sub_f32_e32 v14, v14, v24
	v_add_f32_e32 v31, v66, v67
	s_lshl_b64 s[30:31], s[30:31], 12
	s_add_u32 s30, s4, s30
	v_add_f32_dpp v31, v31, v31 quad_perm:[1,0,3,2] row_mask:0xf bank_mask:0xf bound_ctrl:1
	s_addc_u32 s31, s5, s31
	s_add_i32 s51, s51, s36
	v_add_f32_dpp v31, v31, v31 quad_perm:[2,3,0,1] row_mask:0xf bank_mask:0xf bound_ctrl:1
	s_add_i32 s3, s3, s43
	s_cmp_lt_i32 s51, 0x11000
	v_pk_fma_f32 v[8:9], v[8:9], v[74:75], v[62:63]
	v_pk_fma_f32 v[12:13], v[12:13], v[78:79], v[20:21]
	v_pk_fma_f32 v[16:17], v[16:17], v[82:83], v[22:23]
	v_lshlrev_b32_e32 v20, 16, v56
	v_and_b32_e32 v21, 0xffff0000, v56
	v_lshlrev_b32_e32 v22, 16, v57
	v_and_b32_e32 v23, 0xffff0000, v57
	v_pk_add_f32 v[20:21], v[20:21], -1.0 op_sel_hi:[1,0]
	v_pk_add_f32 v[22:23], v[22:23], -1.0 op_sel_hi:[1,0]
	v_pk_fma_f32 v[10:11], v[10:11], v[76:77], v[64:65]
	v_pk_fma_f32 v[22:23], v[86:87], v[22:23], 1.0 op_sel_hi:[1,1,0]
	v_pk_fma_f32 v[20:21], v[84:85], v[20:21], 1.0 op_sel_hi:[1,1,0]
	v_pk_fma_f32 v[6:7], v[6:7], v[72:73], v[60:61]
	v_pk_mul_f32 v[10:11], v[10:11], v[20:21]
	v_pk_mul_f32 v[12:13], v[12:13], v[22:23]
	v_pk_mul_f32 v[6:7], v[6:7], v[10:11]
	v_pk_mul_f32 v[8:9], v[8:9], v[12:13]
	v_pk_mul_f32 v[6:7], v[88:89], v[6:7]
	v_pk_mul_f32 v[8:9], v[90:91], v[8:9]
	v_pk_fma_f32 v[14:15], v[14:15], v[80:81], v[24:25]
	v_pk_mov_b32 v[10:11], v[6:7], v[8:9] op_sel:[1,0]
	v_mov_b32_e32 v7, v9
	v_pk_add_f32 v[6:7], v[10:11], v[6:7]
	v_lshlrev_b32_e32 v24, 16, v58
	v_add_f32_e32 v6, v6, v7
	v_and_b32_e32 v25, 0xffff0000, v58
	v_lshlrev_b32_e32 v32, 16, v59
	v_add_f32_dpp v7, v6, v6 quad_perm:[1,0,3,2] row_mask:0xf bank_mask:0xf bound_ctrl:1
	v_add_f32_dpp v6, v31, v31 row_half_mirror row_mask:0xf bank_mask:0xf bound_ctrl:1
	v_and_b32_e32 v33, 0xffff0000, v59
	v_add_f32_dpp v7, v7, v7 quad_perm:[2,3,0,1] row_mask:0xf bank_mask:0xf bound_ctrl:1
	v_add_f32_dpp v6, v6, v6 row_mirror row_mask:0xf bank_mask:0xf bound_ctrl:1
	v_fmamk_f32 v6, v6, 0x3c800000, v30
	v_rsq_f32_e32 v6, v6
	v_add_f32_dpp v7, v7, v7 row_half_mirror row_mask:0xf bank_mask:0xf bound_ctrl:1
	v_pk_mul_f32 v[2:3], v[2:3], v[6:7] op_sel_hi:[1,0]
	v_pk_mul_f32 v[4:5], v[4:5], v[6:7] op_sel_hi:[1,0]
	v_add_f32_dpp v8, v7, v7 row_mirror row_mask:0xf bank_mask:0xf bound_ctrl:1
	v_pk_fma_f32 v[4:5], v[94:95], v[4:5], v[98:99]
	v_pk_fma_f32 v[2:3], v[92:93], v[2:3], v[96:97]
	v_pk_fma_f32 v[4:5], v[16:17], v[8:9], v[4:5] op_sel_hi:[1,0,1]
	v_pk_fma_f32 v[2:3], v[14:15], v[8:9], v[2:3] op_sel_hi:[1,0,1]
	v_pk_mul_f32 v[4:5], v[4:5], v[32:33]
	v_pk_mul_f32 v[2:3], v[2:3], v[24:25]
	s_nop 0
	v_cvt_pk_bf16_f32 v2, v2, v3
	v_cvt_pk_bf16_f32 v3, v4, v5
	v_lshl_add_u64 v[4:5], s[30:31], 0, v[18:19]
	v_add_co_u32_e32 v4, vcc, 0x64c0000, v4
	s_nop 1
	v_addc_co_u32_e32 v5, vcc, 0, v5, vcc
	global_store_dwordx2 v[4:5], v[2:3], off offset:2048
	s_cbranch_scc1 .LBB0_918
